# up-GEMM: epilogue row scalars loaded at unit start into freed registers, epilogue vmcnt(0) removed
# baseline (speedup 1.0000x reference)
.LBB0_1143:
	s_ashr_i32 s49, s48, 31
	s_lshl_b64 s[6:7], s[48:49], 19
	s_add_u32 s50, s60, s6
	s_addc_u32 s51, s61, s7
	s_and_b64 s[6:7], s[38:39], exec
	s_cselect_b32 s5, s51, s31
	s_cselect_b32 s6, s50, s30
	s_ashr_i32 s47, s46, 31
	s_lshl_b64 s[8:9], s[46:47], 19
	s_add_u32 s52, s57, s8
	s_addc_u32 s53, s58, s9
	s_and_b64 s[8:9], s[38:39], exec
	s_cselect_b32 s7, s53, s41
	s_cselect_b32 s8, s52, s40
	s_add_u32 s30, s30, 0x40080
	s_addc_u32 s31, s31, 0
	s_add_u32 s9, s40, 0x100
	s_addc_u32 s23, s41, 0
	s_mov_b32 s47, -2
	v_lshl_add_u32 v226, s22, 8, v149
	v_ashrrev_i32_e32 v227, 31, v226
	v_lshl_add_u64 v[226:227], v[226:227], 2, s[34:35]
	global_load_dword v228, v[226:227], off
	global_load_dword v229, v[226:227], off offset:64
	global_load_dword v230, v[226:227], off offset:128
	global_load_dword v231, v[226:227], off offset:192
	global_load_dword v232, v[226:227], off offset:512
	global_load_dword v233, v[226:227], off offset:576
	global_load_dword v190, v[226:227], off offset:640
	global_load_dword v191, v[226:227], off offset:704
	s_add_u32 s10, s30, 0xfffc0080
	s_addc_u32 s11, s31, -1
	s_add_i32 s12, 0, 0x10000
	s_cmp_eq_u32 s47, 12
	s_cselect_b32 s55, s5, s11
	s_cselect_b32 s54, s6, s10
	v_add_u32_e32 v146, s12, v150
	s_cselect_b32 s41, s7, s23
	s_cselect_b32 s40, s8, s9
	s_add_i32 s13, 0, 0x14000
	ds_read_b128 v[138:141], v146
	ds_read_b128 v[142:145], v146 offset:1024
	ds_read_b128 v[154:157], v146 offset:2048
	ds_read_b128 v[158:161], v146 offset:3072
	v_add_u32_e32 v146, s13, v150
	ds_read_b128 v[162:165], v146
	ds_read_b128 v[166:169], v146 offset:1024
	ds_read_b128 v[170:173], v146 offset:2048
	ds_read_b128 v[174:177], v146 offset:3072
	s_add_u32 s10, s30, 0xfffc0000
	s_addc_u32 s11, s31, -1
	s_mov_b32 m0, s26
	s_nop 0
	global_load_lds_dwordx4 v134, s[10:11]
	s_mov_b32 m0, s67
	s_nop 0
	global_load_lds_dwordx4 v136, s[10:11]
	s_add_i32 m0, s63, 0xc000
	ds_read_b128 v[178:181], v152
	ds_read_b128 v[182:185], v152 offset:1024
	ds_read_b128 v[186:189], v152 offset:2048
	ds_read_b128 v[206:209], v152 offset:3072
	ds_read_b128 v[210:213], v152 offset:4096
	ds_read_b128 v[214:217], v152 offset:5120
	ds_read_b128 v[218:221], v152 offset:6144
	ds_read_b128 v[222:225], v152 offset:7168
	global_load_lds_dwordx4 v134, s[30:31]
	s_add_i32 m0, s63, 0xe000
	s_nop 0
	global_load_lds_dwordx4 v136, s[30:31]
	s_waitcnt vmcnt(8)
	s_waitcnt lgkmcnt(0)
	s_barrier
	s_setprio 1
	s_waitcnt lgkmcnt(0)
	v_mfma_f32_16x16x32_bf16 v[124:127], v[138:141], v[178:181], 0
	v_mfma_f32_16x16x32_bf16 v[120:123], v[154:157], v[178:181], 0
	v_mfma_f32_16x16x32_bf16 v[108:111], v[138:141], v[186:189], 0
	v_mfma_f32_16x16x32_bf16 v[104:107], v[154:157], v[186:189], 0
	v_mfma_f32_16x16x32_bf16 v[92:95], v[138:141], v[210:213], 0
	v_mfma_f32_16x16x32_bf16 v[88:91], v[154:157], v[210:213], 0
	v_mfma_f32_16x16x32_bf16 v[76:79], v[138:141], v[218:221], 0
	v_mfma_f32_16x16x32_bf16 v[72:75], v[154:157], v[218:221], 0
	v_mfma_f32_16x16x32_bf16 v[124:127], v[142:145], v[182:185], v[124:127]
	v_mfma_f32_16x16x32_bf16 v[120:123], v[158:161], v[182:185], v[120:123]
	v_mfma_f32_16x16x32_bf16 v[108:111], v[142:145], v[206:209], v[108:111]
	v_mfma_f32_16x16x32_bf16 v[104:107], v[158:161], v[206:209], v[104:107]
	v_mfma_f32_16x16x32_bf16 v[92:95], v[142:145], v[214:217], v[92:95]
	v_mfma_f32_16x16x32_bf16 v[88:91], v[158:161], v[214:217], v[88:91]
	v_mfma_f32_16x16x32_bf16 v[76:79], v[142:145], v[222:225], v[76:79]
	v_mfma_f32_16x16x32_bf16 v[72:75], v[158:161], v[222:225], v[72:75]
	s_setprio 0
	s_setprio 1
	v_mfma_f32_16x16x32_bf16 v[116:119], v[162:165], v[178:181], 0
	v_mfma_f32_16x16x32_bf16 v[112:115], v[170:173], v[178:181], 0
	v_mfma_f32_16x16x32_bf16 v[100:103], v[162:165], v[186:189], 0
	v_mfma_f32_16x16x32_bf16 v[96:99], v[170:173], v[186:189], 0
	v_mfma_f32_16x16x32_bf16 v[84:87], v[162:165], v[210:213], 0
	v_mfma_f32_16x16x32_bf16 v[80:83], v[170:173], v[210:213], 0
	v_mfma_f32_16x16x32_bf16 v[68:71], v[162:165], v[218:221], 0
	v_mfma_f32_16x16x32_bf16 v[64:67], v[170:173], v[218:221], 0
	v_mfma_f32_16x16x32_bf16 v[116:119], v[166:169], v[182:185], v[116:119]
	v_mfma_f32_16x16x32_bf16 v[112:115], v[174:177], v[182:185], v[112:115]
	v_mfma_f32_16x16x32_bf16 v[100:103], v[166:169], v[206:209], v[100:103]
	v_mfma_f32_16x16x32_bf16 v[96:99], v[174:177], v[206:209], v[96:99]
	v_mfma_f32_16x16x32_bf16 v[84:87], v[166:169], v[214:217], v[84:87]
	v_mfma_f32_16x16x32_bf16 v[80:83], v[174:177], v[214:217], v[80:83]
	v_mfma_f32_16x16x32_bf16 v[68:71], v[166:169], v[222:225], v[68:71]
	v_mfma_f32_16x16x32_bf16 v[64:67], v[174:177], v[222:225], v[64:67]
	s_setprio 0
	s_barrier
	s_add_i32 s10, s12, s62
	s_mov_b32 m0, s10
	ds_read_b128 v[178:181], v152 offset:16384
	ds_read_b128 v[182:185], v152 offset:17408
	ds_read_b128 v[186:189], v152 offset:18432
	ds_read_b128 v[206:209], v152 offset:19456
	ds_read_b128 v[210:213], v152 offset:20480
	ds_read_b128 v[214:217], v152 offset:21504
	ds_read_b128 v[218:221], v152 offset:22528
	ds_read_b128 v[222:225], v152 offset:23552
	global_load_lds_dwordx4 v192, s[40:41]
	s_add_i32 m0, s10, 0x2000
	s_add_u32 s10, s40, 0x40000
	s_addc_u32 s11, s41, 0
	s_add_i32 s12, s13, s62
	global_load_lds_dwordx4 v132, s[40:41]
	s_mov_b32 m0, s12
	s_nop 0
	global_load_lds_dwordx4 v192, s[10:11]
	s_add_i32 m0, s12, 0x2000
	s_nop 0
	global_load_lds_dwordx4 v132, s[10:11]
	s_waitcnt vmcnt(6)
	s_waitcnt lgkmcnt(0)
	s_barrier
	s_setprio 1
	s_waitcnt lgkmcnt(0)
	v_mfma_f32_16x16x32_bf16 v[60:63], v[138:141], v[178:181], 0
	v_mfma_f32_16x16x32_bf16 v[56:59], v[154:157], v[178:181], 0
	v_mfma_f32_16x16x32_bf16 v[44:47], v[138:141], v[186:189], 0
	v_mfma_f32_16x16x32_bf16 v[40:43], v[154:157], v[186:189], 0
	v_mfma_f32_16x16x32_bf16 v[28:31], v[138:141], v[210:213], 0
	v_mfma_f32_16x16x32_bf16 v[24:27], v[154:157], v[210:213], 0
	v_mfma_f32_16x16x32_bf16 v[12:15], v[138:141], v[218:221], 0
	v_mfma_f32_16x16x32_bf16 v[8:11], v[154:157], v[218:221], 0
	v_mfma_f32_16x16x32_bf16 v[60:63], v[142:145], v[182:185], v[60:63]
	v_mfma_f32_16x16x32_bf16 v[56:59], v[158:161], v[182:185], v[56:59]
	v_mfma_f32_16x16x32_bf16 v[44:47], v[142:145], v[206:209], v[44:47]
	v_mfma_f32_16x16x32_bf16 v[40:43], v[158:161], v[206:209], v[40:43]
	v_mfma_f32_16x16x32_bf16 v[28:31], v[142:145], v[214:217], v[28:31]
	v_mfma_f32_16x16x32_bf16 v[24:27], v[158:161], v[214:217], v[24:27]
	v_mfma_f32_16x16x32_bf16 v[12:15], v[142:145], v[222:225], v[12:15]
	v_mfma_f32_16x16x32_bf16 v[8:11], v[158:161], v[222:225], v[8:11]
	s_setprio 0
	s_setprio 1
	v_mfma_f32_16x16x32_bf16 v[52:55], v[162:165], v[178:181], 0
	v_mfma_f32_16x16x32_bf16 v[48:51], v[170:173], v[178:181], 0
	v_mfma_f32_16x16x32_bf16 v[36:39], v[162:165], v[186:189], 0
	v_mfma_f32_16x16x32_bf16 v[32:35], v[170:173], v[186:189], 0
	v_mfma_f32_16x16x32_bf16 v[20:23], v[162:165], v[210:213], 0
	v_mfma_f32_16x16x32_bf16 v[16:19], v[170:173], v[210:213], 0
	v_mfma_f32_16x16x32_bf16 v[4:7], v[162:165], v[218:221], 0
	v_mfma_f32_16x16x32_bf16 v[0:3], v[170:173], v[218:221], 0
	v_mfma_f32_16x16x32_bf16 v[52:55], v[166:169], v[182:185], v[52:55]
	v_mfma_f32_16x16x32_bf16 v[48:51], v[174:177], v[182:185], v[48:51]
	v_mfma_f32_16x16x32_bf16 v[36:39], v[166:169], v[206:209], v[36:39]
	v_mfma_f32_16x16x32_bf16 v[32:35], v[174:177], v[206:209], v[32:35]
	v_mfma_f32_16x16x32_bf16 v[20:23], v[166:169], v[214:217], v[20:23]
	v_mfma_f32_16x16x32_bf16 v[16:19], v[174:177], v[214:217], v[16:19]
	v_mfma_f32_16x16x32_bf16 v[4:7], v[166:169], v[222:225], v[4:7]
	v_mfma_f32_16x16x32_bf16 v[0:3], v[174:177], v[222:225], v[0:3]
	s_setprio 0
	s_barrier
	s_add_i32 s12, 0, 0x18000
	v_add_u32_e32 v146, s12, v150
	s_add_i32 s13, 0, 0x1c000
	ds_read_b128 v[138:141], v146
	ds_read_b128 v[142:145], v146 offset:1024
	ds_read_b128 v[154:157], v146 offset:2048
	ds_read_b128 v[158:161], v146 offset:3072
	v_add_u32_e32 v146, s13, v150
	ds_read_b128 v[162:165], v146
	ds_read_b128 v[166:169], v146 offset:1024
	ds_read_b128 v[170:173], v146 offset:2048
	ds_read_b128 v[174:177], v146 offset:3072
	s_mov_b32 m0, s63
	s_nop 0
	global_load_lds_dwordx4 v128, s[54:55]
	s_mov_b32 m0, s64
	s_nop 0
	global_load_lds_dwordx4 v130, s[54:55]
	s_add_u32 s10, s54, 0x40000
	s_addc_u32 s11, s55, 0
	s_mov_b32 m0, s65
	ds_read_b128 v[178:181], v152 offset:32768
	ds_read_b128 v[182:185], v152 offset:33792
	ds_read_b128 v[186:189], v152 offset:34816
	ds_read_b128 v[206:209], v152 offset:35840
	ds_read_b128 v[210:213], v152 offset:36864
	ds_read_b128 v[214:217], v152 offset:37888
	ds_read_b128 v[218:221], v152 offset:38912
	ds_read_b128 v[222:225], v152 offset:39936
	global_load_lds_dwordx4 v128, s[10:11]
	s_mov_b32 m0, s66
	s_nop 0
	global_load_lds_dwordx4 v130, s[10:11]
	s_waitcnt vmcnt(8)
	s_waitcnt lgkmcnt(0)
	s_barrier
	s_setprio 1
	s_waitcnt lgkmcnt(0)
	v_mfma_f32_16x16x32_bf16 v[124:127], v[138:141], v[178:181], v[124:127]
	v_mfma_f32_16x16x32_bf16 v[120:123], v[154:157], v[178:181], v[120:123]
	v_mfma_f32_16x16x32_bf16 v[108:111], v[138:141], v[186:189], v[108:111]
	v_mfma_f32_16x16x32_bf16 v[104:107], v[154:157], v[186:189], v[104:107]
	v_mfma_f32_16x16x32_bf16 v[92:95], v[138:141], v[210:213], v[92:95]
	v_mfma_f32_16x16x32_bf16 v[88:91], v[154:157], v[210:213], v[88:91]
	v_mfma_f32_16x16x32_bf16 v[76:79], v[138:141], v[218:221], v[76:79]
	v_mfma_f32_16x16x32_bf16 v[72:75], v[154:157], v[218:221], v[72:75]
	v_mfma_f32_16x16x32_bf16 v[124:127], v[142:145], v[182:185], v[124:127]
	v_mfma_f32_16x16x32_bf16 v[120:123], v[158:161], v[182:185], v[120:123]
	v_mfma_f32_16x16x32_bf16 v[108:111], v[142:145], v[206:209], v[108:111]
	v_mfma_f32_16x16x32_bf16 v[104:107], v[158:161], v[206:209], v[104:107]
	v_mfma_f32_16x16x32_bf16 v[92:95], v[142:145], v[214:217], v[92:95]
	v_mfma_f32_16x16x32_bf16 v[88:91], v[158:161], v[214:217], v[88:91]
	v_mfma_f32_16x16x32_bf16 v[76:79], v[142:145], v[222:225], v[76:79]
	v_mfma_f32_16x16x32_bf16 v[72:75], v[158:161], v[222:225], v[72:75]
	s_setprio 0
	s_setprio 1
	v_mfma_f32_16x16x32_bf16 v[116:119], v[162:165], v[178:181], v[116:119]
	v_mfma_f32_16x16x32_bf16 v[112:115], v[170:173], v[178:181], v[112:115]
	v_mfma_f32_16x16x32_bf16 v[100:103], v[162:165], v[186:189], v[100:103]
	v_mfma_f32_16x16x32_bf16 v[96:99], v[170:173], v[186:189], v[96:99]
	v_mfma_f32_16x16x32_bf16 v[84:87], v[162:165], v[210:213], v[84:87]
	v_mfma_f32_16x16x32_bf16 v[80:83], v[170:173], v[210:213], v[80:83]
	v_mfma_f32_16x16x32_bf16 v[68:71], v[162:165], v[218:221], v[68:71]
	v_mfma_f32_16x16x32_bf16 v[64:67], v[170:173], v[218:221], v[64:67]
	v_mfma_f32_16x16x32_bf16 v[116:119], v[166:169], v[182:185], v[116:119]
	v_mfma_f32_16x16x32_bf16 v[112:115], v[174:177], v[182:185], v[112:115]
	v_mfma_f32_16x16x32_bf16 v[100:103], v[166:169], v[206:209], v[100:103]
	v_mfma_f32_16x16x32_bf16 v[96:99], v[174:177], v[206:209], v[96:99]
	v_mfma_f32_16x16x32_bf16 v[84:87], v[166:169], v[214:217], v[84:87]
	v_mfma_f32_16x16x32_bf16 v[80:83], v[174:177], v[214:217], v[80:83]
	v_mfma_f32_16x16x32_bf16 v[68:71], v[166:169], v[222:225], v[68:71]
	v_mfma_f32_16x16x32_bf16 v[64:67], v[174:177], v[222:225], v[64:67]
	s_setprio 0
	s_barrier
	s_add_i32 s10, s12, s62
	s_add_i32 m0, s10, 0xffffff80
	ds_read_b128 v[178:181], v152 offset:49152
	ds_read_b128 v[182:185], v152 offset:50176
	ds_read_b128 v[186:189], v152 offset:51200
	ds_read_b128 v[206:209], v152 offset:52224
	ds_read_b128 v[210:213], v152 offset:53248
	ds_read_b128 v[214:217], v152 offset:54272
	ds_read_b128 v[218:221], v152 offset:55296
	ds_read_b128 v[222:225], v152 offset:56320
	global_load_lds_dwordx4 v192, s[40:41] offset:128
	s_add_i32 m0, s10, 0x1f80
	s_add_u32 s10, s40, 0x40080
	s_addc_u32 s11, s41, 0
	s_add_i32 s12, s13, s62
	global_load_lds_dwordx4 v132, s[40:41] offset:128
	s_mov_b32 m0, s12
	s_nop 0
	global_load_lds_dwordx4 v192, s[10:11]
	s_add_i32 m0, s12, 0x2000
	s_nop 0
	global_load_lds_dwordx4 v132, s[10:11]
	s_waitcnt vmcnt(6)
	s_waitcnt lgkmcnt(0)
	s_barrier
	s_setprio 1
	s_waitcnt lgkmcnt(0)
	v_mfma_f32_16x16x32_bf16 v[60:63], v[138:141], v[178:181], v[60:63]
	v_mfma_f32_16x16x32_bf16 v[56:59], v[154:157], v[178:181], v[56:59]
	v_mfma_f32_16x16x32_bf16 v[44:47], v[138:141], v[186:189], v[44:47]
	v_mfma_f32_16x16x32_bf16 v[40:43], v[154:157], v[186:189], v[40:43]
	v_mfma_f32_16x16x32_bf16 v[28:31], v[138:141], v[210:213], v[28:31]
	v_mfma_f32_16x16x32_bf16 v[24:27], v[154:157], v[210:213], v[24:27]
	v_mfma_f32_16x16x32_bf16 v[12:15], v[138:141], v[218:221], v[12:15]
	v_mfma_f32_16x16x32_bf16 v[8:11], v[154:157], v[218:221], v[8:11]
	v_mfma_f32_16x16x32_bf16 v[60:63], v[142:145], v[182:185], v[60:63]
	v_mfma_f32_16x16x32_bf16 v[56:59], v[158:161], v[182:185], v[56:59]
	v_mfma_f32_16x16x32_bf16 v[44:47], v[142:145], v[206:209], v[44:47]
	v_mfma_f32_16x16x32_bf16 v[40:43], v[158:161], v[206:209], v[40:43]
	v_mfma_f32_16x16x32_bf16 v[28:31], v[142:145], v[214:217], v[28:31]
	v_mfma_f32_16x16x32_bf16 v[24:27], v[158:161], v[214:217], v[24:27]
	v_mfma_f32_16x16x32_bf16 v[12:15], v[142:145], v[222:225], v[12:15]
	v_mfma_f32_16x16x32_bf16 v[8:11], v[158:161], v[222:225], v[8:11]
	s_setprio 0
	s_setprio 1
	v_mfma_f32_16x16x32_bf16 v[52:55], v[162:165], v[178:181], v[52:55]
	v_mfma_f32_16x16x32_bf16 v[48:51], v[170:173], v[178:181], v[48:51]
	v_mfma_f32_16x16x32_bf16 v[36:39], v[162:165], v[186:189], v[36:39]
	v_mfma_f32_16x16x32_bf16 v[32:35], v[170:173], v[186:189], v[32:35]
	v_mfma_f32_16x16x32_bf16 v[20:23], v[162:165], v[210:213], v[20:23]
	v_mfma_f32_16x16x32_bf16 v[16:19], v[170:173], v[210:213], v[16:19]
	v_mfma_f32_16x16x32_bf16 v[4:7], v[162:165], v[218:221], v[4:7]
	v_mfma_f32_16x16x32_bf16 v[0:3], v[170:173], v[218:221], v[0:3]
	v_mfma_f32_16x16x32_bf16 v[52:55], v[166:169], v[182:185], v[52:55]
	v_mfma_f32_16x16x32_bf16 v[48:51], v[174:177], v[182:185], v[48:51]
	v_mfma_f32_16x16x32_bf16 v[36:39], v[166:169], v[206:209], v[36:39]
	v_mfma_f32_16x16x32_bf16 v[32:35], v[174:177], v[206:209], v[32:35]
	v_mfma_f32_16x16x32_bf16 v[20:23], v[166:169], v[214:217], v[20:23]
	v_mfma_f32_16x16x32_bf16 v[16:19], v[174:177], v[214:217], v[16:19]
	v_mfma_f32_16x16x32_bf16 v[4:7], v[166:169], v[222:225], v[4:7]
	v_mfma_f32_16x16x32_bf16 v[0:3], v[174:177], v[222:225], v[0:3]
	s_setprio 0
	s_barrier
	s_add_i32 s47, s47, 2
	s_add_u32 s30, s30, 0x100
	s_addc_u32 s31, s31, 0
	s_add_u32 s9, s9, 0x100
	s_addc_u32 s23, s23, 0
	s_cmp_gt_u32 s47, 13

.LBB0_1147:
	v_lshl_add_u32 v144, s22, 8, v149
	v_ashrrev_i32_e32 v145, 31, v144
	v_lshl_add_u64 v[138:139], v[144:145], 2, s[34:35]
	v_mov_b32_e32 v142, v228
	v_mov_b32_e32 v164, v229
	v_mov_b32_e32 v165, v230
	v_mov_b32_e32 v166, v231
	v_mov_b32_e32 v167, v232
	v_mov_b32_e32 v168, v233
	v_mov_b32_e32 v169, v190
	v_mov_b32_e32 v170, v191
	v_lshl_or_b32 v140, s4, 8, v151
	v_ashrrev_i32_e32 v141, 31, v140
	s_mov_b64 s[22:23], -1
	v_fmamk_f32 v142, v142, 0x3a800000, v235
	v_rsq_f32_e32 v146, v142
	s_nop 0
	v_pk_mul_f32 v[120:121], v[120:121], v[146:147] op_sel_hi:[1,0]
	v_pk_mul_f32 v[124:125], v[124:125], v[146:147] op_sel_hi:[1,0]
	v_pk_mul_f32 v[122:123], v[122:123], v[146:147] op_sel_hi:[1,0]
	v_max_f32_e32 v120, 0, v120
	v_lshlrev_b64 v[142:143], 13, v[144:145]
	v_pk_mul_f32 v[126:127], v[126:127], v[146:147] op_sel_hi:[1,0]
	v_mul_f32_e32 v145, v120, v120
	v_max_f32_e32 v120, 0, v125
	v_max_f32_e32 v121, 0, v121
	v_max_f32_e32 v122, 0, v122
	v_lshl_add_u64 v[154:155], s[36:37], 0, v[142:143]
	v_lshlrev_b64 v[142:143], 1, v[140:141]
	v_max_f32_e32 v124, 0, v124
	v_mul_f32_e32 v120, v120, v120
	v_mul_f32_e32 v125, v121, v121
	v_max_f32_e32 v121, 0, v126
	v_mul_f32_e32 v126, v122, v122
	v_max_f32_e32 v122, 0, v127
	v_max_f32_e32 v123, 0, v123
	v_pk_mul_f32 v[114:115], v[114:115], v[146:147] op_sel_hi:[1,0]
	v_pk_mul_f32 v[112:113], v[112:113], v[146:147] op_sel_hi:[1,0]
	v_lshl_add_u64 v[140:141], v[154:155], 0, v[142:143]
	v_mul_f32_e32 v124, v124, v124
	v_mul_f32_e32 v121, v121, v121
	v_mul_f32_e32 v122, v122, v122
	v_mul_f32_e32 v123, v123, v123
	v_cvt_pk_bf16_f32 v120, v124, v120
	v_pk_mul_f32 v[118:119], v[118:119], v[146:147] op_sel_hi:[1,0]
	v_pk_mul_f32 v[116:117], v[116:117], v[146:147] op_sel_hi:[1,0]
	v_max_f32_e32 v112, 0, v112
	v_max_f32_e32 v113, 0, v113
	v_max_f32_e32 v114, 0, v114
	v_cvt_pk_bf16_f32 v121, v121, v122
	v_cvt_pk_bf16_f32 v122, v145, v125
	v_cvt_pk_bf16_f32 v123, v126, v123
	global_store_dwordx4 v[140:141], v[120:123], off
	v_max_f32_e32 v115, 0, v115
	v_max_f32_e32 v116, 0, v116
	v_mul_f32_e32 v120, v112, v112
	v_max_f32_e32 v112, 0, v117
	v_mul_f32_e32 v117, v113, v113
	v_max_f32_e32 v113, 0, v118
	v_mul_f32_e32 v118, v114, v114
	v_max_f32_e32 v114, 0, v119
	v_mul_f32_e32 v112, v112, v112
	v_mul_f32_e32 v113, v113, v113
	v_mul_f32_e32 v114, v114, v114
	v_mul_f32_e32 v115, v115, v115
	v_mul_f32_e32 v116, v116, v116
	v_cvt_pk_bf16_f32 v112, v116, v112
	v_cvt_pk_bf16_f32 v113, v113, v114
	v_cvt_pk_bf16_f32 v114, v120, v117
	v_cvt_pk_bf16_f32 v115, v118, v115
	global_store_dwordx4 v[140:141], v[112:115], off offset:256
	s_nop 1
	v_mov_b32_e32 v112, v164
	s_nop 0
	v_or_b32_e32 v114, 16, v144
	v_ashrrev_i32_e32 v115, 31, v114
	v_lshlrev_b64 v[114:115], 13, v[114:115]
	v_lshl_add_u64 v[114:115], s[36:37], 0, v[114:115]
	v_lshl_add_u64 v[114:115], v[114:115], 0, v[142:143]
	v_fmamk_f32 v112, v112, 0x3a800000, v235
	v_rsq_f32_e32 v112, v112
	s_nop 0
	v_pk_mul_f32 v[104:105], v[104:105], v[112:113] op_sel_hi:[1,0]
	v_pk_mul_f32 v[108:109], v[108:109], v[112:113] op_sel_hi:[1,0]
	v_pk_mul_f32 v[106:107], v[106:107], v[112:113] op_sel_hi:[1,0]
	v_max_f32_e32 v104, 0, v104
	v_pk_mul_f32 v[110:111], v[110:111], v[112:113] op_sel_hi:[1,0]
	v_mul_f32_e32 v113, v104, v104
	v_max_f32_e32 v104, 0, v109
	v_max_f32_e32 v105, 0, v105
	v_max_f32_e32 v106, 0, v106
	v_max_f32_e32 v108, 0, v108
	v_mul_f32_e32 v104, v104, v104
	v_mul_f32_e32 v109, v105, v105
	v_max_f32_e32 v105, 0, v110
	v_mul_f32_e32 v110, v106, v106
	v_max_f32_e32 v106, 0, v111
	v_max_f32_e32 v107, 0, v107
	v_pk_mul_f32 v[98:99], v[98:99], v[112:113] op_sel_hi:[1,0]
	v_pk_mul_f32 v[96:97], v[96:97], v[112:113] op_sel_hi:[1,0]
	v_mul_f32_e32 v108, v108, v108
	v_mul_f32_e32 v105, v105, v105
	v_mul_f32_e32 v106, v106, v106
	v_mul_f32_e32 v107, v107, v107
	v_cvt_pk_bf16_f32 v104, v108, v104
	v_pk_mul_f32 v[102:103], v[102:103], v[112:113] op_sel_hi:[1,0]
	v_pk_mul_f32 v[100:101], v[100:101], v[112:113] op_sel_hi:[1,0]
	v_max_f32_e32 v96, 0, v96
	v_max_f32_e32 v97, 0, v97
	v_max_f32_e32 v98, 0, v98
	v_cvt_pk_bf16_f32 v105, v105, v106
	v_cvt_pk_bf16_f32 v106, v113, v109
	v_cvt_pk_bf16_f32 v107, v110, v107
	global_store_dwordx4 v[114:115], v[104:107], off
	v_max_f32_e32 v99, 0, v99
	v_max_f32_e32 v100, 0, v100
	v_mul_f32_e32 v104, v96, v96
	v_max_f32_e32 v96, 0, v101
	v_mul_f32_e32 v101, v97, v97
	v_max_f32_e32 v97, 0, v102
	v_mul_f32_e32 v102, v98, v98
	v_max_f32_e32 v98, 0, v103
	v_mul_f32_e32 v96, v96, v96
	v_mul_f32_e32 v97, v97, v97
	v_mul_f32_e32 v98, v98, v98
	v_mul_f32_e32 v99, v99, v99
	v_mul_f32_e32 v100, v100, v100
	v_cvt_pk_bf16_f32 v96, v100, v96
	v_cvt_pk_bf16_f32 v97, v97, v98
	v_cvt_pk_bf16_f32 v98, v104, v101
	v_cvt_pk_bf16_f32 v99, v102, v99
	global_store_dwordx4 v[114:115], v[96:99], off offset:256
	s_nop 1
	v_mov_b32_e32 v96, v165
	s_nop 0
	v_or_b32_e32 v98, 32, v144
	v_ashrrev_i32_e32 v99, 31, v98
	v_lshlrev_b64 v[98:99], 13, v[98:99]
	v_lshl_add_u64 v[98:99], s[36:37], 0, v[98:99]
	v_lshl_add_u64 v[98:99], v[98:99], 0, v[142:143]
	v_fmamk_f32 v96, v96, 0x3a800000, v235
	v_rsq_f32_e32 v96, v96
	s_nop 0
	v_pk_mul_f32 v[88:89], v[88:89], v[96:97] op_sel_hi:[1,0]
	v_pk_mul_f32 v[92:93], v[92:93], v[96:97] op_sel_hi:[1,0]
	v_pk_mul_f32 v[90:91], v[90:91], v[96:97] op_sel_hi:[1,0]
	v_max_f32_e32 v88, 0, v88
	v_pk_mul_f32 v[94:95], v[94:95], v[96:97] op_sel_hi:[1,0]
	v_mul_f32_e32 v97, v88, v88
	v_max_f32_e32 v88, 0, v93
	v_max_f32_e32 v89, 0, v89
	v_max_f32_e32 v90, 0, v90
	v_max_f32_e32 v92, 0, v92
	v_mul_f32_e32 v88, v88, v88
	v_mul_f32_e32 v93, v89, v89
	v_max_f32_e32 v89, 0, v94
	v_mul_f32_e32 v94, v90, v90
	v_max_f32_e32 v90, 0, v95
	v_max_f32_e32 v91, 0, v91
	v_pk_mul_f32 v[82:83], v[82:83], v[96:97] op_sel_hi:[1,0]
	v_pk_mul_f32 v[80:81], v[80:81], v[96:97] op_sel_hi:[1,0]
	v_mul_f32_e32 v92, v92, v92
	v_mul_f32_e32 v89, v89, v89
	v_mul_f32_e32 v90, v90, v90
	v_mul_f32_e32 v91, v91, v91
	v_cvt_pk_bf16_f32 v88, v92, v88
	v_pk_mul_f32 v[86:87], v[86:87], v[96:97] op_sel_hi:[1,0]
	v_pk_mul_f32 v[84:85], v[84:85], v[96:97] op_sel_hi:[1,0]
	v_max_f32_e32 v80, 0, v80
	v_max_f32_e32 v81, 0, v81
	v_max_f32_e32 v82, 0, v82
	v_cvt_pk_bf16_f32 v89, v89, v90
	v_cvt_pk_bf16_f32 v90, v97, v93
	v_cvt_pk_bf16_f32 v91, v94, v91
	global_store_dwordx4 v[98:99], v[88:91], off
	v_max_f32_e32 v83, 0, v83
	v_max_f32_e32 v84, 0, v84
	v_mul_f32_e32 v88, v80, v80
	v_max_f32_e32 v80, 0, v85
	v_mul_f32_e32 v85, v81, v81
	v_max_f32_e32 v81, 0, v86
	v_mul_f32_e32 v86, v82, v82
	v_max_f32_e32 v82, 0, v87
	v_mul_f32_e32 v80, v80, v80
	v_mul_f32_e32 v81, v81, v81
	v_mul_f32_e32 v82, v82, v82
	v_mul_f32_e32 v83, v83, v83
	v_mul_f32_e32 v84, v84, v84
	v_cvt_pk_bf16_f32 v80, v84, v80
	v_cvt_pk_bf16_f32 v81, v81, v82
	v_cvt_pk_bf16_f32 v82, v88, v85
	v_cvt_pk_bf16_f32 v83, v86, v83
	global_store_dwordx4 v[98:99], v[80:83], off offset:256
	s_nop 1
	v_mov_b32_e32 v80, v166
	s_nop 0
	v_or_b32_e32 v82, 48, v144
	v_ashrrev_i32_e32 v83, 31, v82
	v_lshlrev_b64 v[82:83], 13, v[82:83]
	v_lshl_add_u64 v[82:83], s[36:37], 0, v[82:83]
	v_lshl_add_u64 v[82:83], v[82:83], 0, v[142:143]
	v_fmamk_f32 v80, v80, 0x3a800000, v235
	v_rsq_f32_e32 v80, v80
	s_nop 0
	v_pk_mul_f32 v[72:73], v[72:73], v[80:81] op_sel_hi:[1,0]
	v_pk_mul_f32 v[76:77], v[76:77], v[80:81] op_sel_hi:[1,0]
	v_pk_mul_f32 v[74:75], v[74:75], v[80:81] op_sel_hi:[1,0]
	v_max_f32_e32 v72, 0, v72
	v_pk_mul_f32 v[78:79], v[78:79], v[80:81] op_sel_hi:[1,0]
	v_mul_f32_e32 v81, v72, v72
	v_max_f32_e32 v72, 0, v77
	v_max_f32_e32 v73, 0, v73
	v_max_f32_e32 v74, 0, v74
	v_max_f32_e32 v76, 0, v76
	v_mul_f32_e32 v72, v72, v72
	v_mul_f32_e32 v77, v73, v73
	v_max_f32_e32 v73, 0, v78
	v_mul_f32_e32 v78, v74, v74
	v_max_f32_e32 v74, 0, v79
	v_max_f32_e32 v75, 0, v75
	v_pk_mul_f32 v[66:67], v[66:67], v[80:81] op_sel_hi:[1,0]
	v_pk_mul_f32 v[64:65], v[64:65], v[80:81] op_sel_hi:[1,0]
	v_mul_f32_e32 v76, v76, v76
	v_mul_f32_e32 v73, v73, v73
	v_mul_f32_e32 v74, v74, v74
	v_mul_f32_e32 v75, v75, v75
	v_cvt_pk_bf16_f32 v72, v76, v72
	v_pk_mul_f32 v[70:71], v[70:71], v[80:81] op_sel_hi:[1,0]
	v_pk_mul_f32 v[68:69], v[68:69], v[80:81] op_sel_hi:[1,0]
	v_max_f32_e32 v64, 0, v64
	v_max_f32_e32 v65, 0, v65
	v_max_f32_e32 v66, 0, v66
	v_cvt_pk_bf16_f32 v73, v73, v74
	v_cvt_pk_bf16_f32 v74, v81, v77
	v_cvt_pk_bf16_f32 v75, v78, v75
	global_store_dwordx4 v[82:83], v[72:75], off
	v_max_f32_e32 v67, 0, v67
	v_max_f32_e32 v68, 0, v68
	v_mul_f32_e32 v72, v64, v64
	v_max_f32_e32 v64, 0, v69
	v_mul_f32_e32 v69, v65, v65
	v_max_f32_e32 v65, 0, v70
	v_mul_f32_e32 v70, v66, v66
	v_max_f32_e32 v66, 0, v71
	v_mul_f32_e32 v64, v64, v64
	v_mul_f32_e32 v65, v65, v65
	v_mul_f32_e32 v66, v66, v66
	v_mul_f32_e32 v67, v67, v67
	v_mul_f32_e32 v68, v68, v68
	v_cvt_pk_bf16_f32 v64, v68, v64
	v_cvt_pk_bf16_f32 v65, v65, v66
	v_cvt_pk_bf16_f32 v66, v72, v69
	v_cvt_pk_bf16_f32 v67, v70, v67
	global_store_dwordx4 v[82:83], v[64:67], off offset:256
	s_nop 1
	v_mov_b32_e32 v64, v167
	v_fmamk_f32 v64, v64, 0x3a800000, v235
	s_mov_b64 s[4:5], 0x100000
	v_rsq_f32_e32 v66, v64
	s_nop 0
	v_pk_mul_f32 v[56:57], v[56:57], v[66:67] op_sel_hi:[1,0]
	v_pk_mul_f32 v[60:61], v[60:61], v[66:67] op_sel_hi:[1,0]
	v_pk_mul_f32 v[58:59], v[58:59], v[66:67] op_sel_hi:[1,0]
	v_max_f32_e32 v56, 0, v56
	v_pk_mul_f32 v[62:63], v[62:63], v[66:67] op_sel_hi:[1,0]
	v_max_f32_e32 v60, 0, v60
	v_mul_f32_e32 v67, v56, v56
	v_max_f32_e32 v56, 0, v61
	v_max_f32_e32 v57, 0, v57
	v_max_f32_e32 v58, 0, v58
	v_lshl_add_u64 v[64:65], v[140:141], 0, s[4:5]
	v_mul_f32_e32 v60, v60, v60
	v_mul_f32_e32 v56, v56, v56
	v_mul_f32_e32 v61, v57, v57
	v_max_f32_e32 v57, 0, v62
	v_mul_f32_e32 v62, v58, v58
	v_max_f32_e32 v58, 0, v63
	s_mov_b32 s4, 0x100000
	v_mul_f32_e32 v57, v57, v57
	v_max_f32_e32 v59, 0, v59
	v_mul_f32_e32 v58, v58, v58
	v_cvt_pk_bf16_f32 v56, v60, v56
	v_add_co_u32_e32 v60, vcc, s4, v140
	v_pk_mul_f32 v[50:51], v[50:51], v[66:67] op_sel_hi:[1,0]
	v_pk_mul_f32 v[48:49], v[48:49], v[66:67] op_sel_hi:[1,0]
	v_mul_f32_e32 v59, v59, v59
	v_cvt_pk_bf16_f32 v57, v57, v58
	v_cvt_pk_bf16_f32 v58, v67, v61
	v_addc_co_u32_e32 v61, vcc, 0, v141, vcc
	v_pk_mul_f32 v[54:55], v[54:55], v[66:67] op_sel_hi:[1,0]
	v_pk_mul_f32 v[52:53], v[52:53], v[66:67] op_sel_hi:[1,0]
	v_max_f32_e32 v48, 0, v48
	v_max_f32_e32 v49, 0, v49
	v_max_f32_e32 v50, 0, v50
	v_cvt_pk_bf16_f32 v59, v62, v59
	global_store_dwordx4 v[60:61], v[56:59], off
	v_max_f32_e32 v51, 0, v51
	v_max_f32_e32 v52, 0, v52
	v_mul_f32_e32 v56, v48, v48
	v_max_f32_e32 v48, 0, v53
	v_mul_f32_e32 v53, v49, v49
	v_max_f32_e32 v49, 0, v54
	v_mul_f32_e32 v54, v50, v50
	v_max_f32_e32 v50, 0, v55
	v_mul_f32_e32 v48, v48, v48
	v_mul_f32_e32 v49, v49, v49
	v_mul_f32_e32 v50, v50, v50
	v_mul_f32_e32 v51, v51, v51
	v_mul_f32_e32 v52, v52, v52
	v_cvt_pk_bf16_f32 v48, v52, v48
	v_cvt_pk_bf16_f32 v49, v49, v50
	v_cvt_pk_bf16_f32 v50, v56, v53
	v_cvt_pk_bf16_f32 v51, v54, v51
	global_store_dwordx4 v[64:65], v[48:51], off offset:256
	s_nop 1
	v_mov_b32_e32 v48, v168
	v_fmamk_f32 v48, v48, 0x3a800000, v235
	s_mov_b64 s[4:5], 0x120000
	v_rsq_f32_e32 v50, v48
	s_nop 0
	v_pk_mul_f32 v[40:41], v[40:41], v[50:51] op_sel_hi:[1,0]
	v_pk_mul_f32 v[44:45], v[44:45], v[50:51] op_sel_hi:[1,0]
	v_pk_mul_f32 v[42:43], v[42:43], v[50:51] op_sel_hi:[1,0]
	v_max_f32_e32 v40, 0, v40
	v_pk_mul_f32 v[46:47], v[46:47], v[50:51] op_sel_hi:[1,0]
	v_max_f32_e32 v44, 0, v44
	v_mul_f32_e32 v51, v40, v40
	v_max_f32_e32 v40, 0, v45
	v_max_f32_e32 v41, 0, v41
	v_max_f32_e32 v42, 0, v42
	v_lshl_add_u64 v[48:49], v[140:141], 0, s[4:5]
	v_mul_f32_e32 v44, v44, v44
	v_mul_f32_e32 v40, v40, v40
	v_mul_f32_e32 v45, v41, v41
	v_max_f32_e32 v41, 0, v46
	v_mul_f32_e32 v46, v42, v42
	v_max_f32_e32 v42, 0, v47
	s_mov_b32 s4, 0x120000
	v_mul_f32_e32 v41, v41, v41
	v_max_f32_e32 v43, 0, v43
	v_mul_f32_e32 v42, v42, v42
	v_cvt_pk_bf16_f32 v40, v44, v40
	v_add_co_u32_e32 v44, vcc, s4, v140
	v_pk_mul_f32 v[34:35], v[34:35], v[50:51] op_sel_hi:[1,0]
	v_pk_mul_f32 v[32:33], v[32:33], v[50:51] op_sel_hi:[1,0]
	v_mul_f32_e32 v43, v43, v43
	v_cvt_pk_bf16_f32 v41, v41, v42
	v_cvt_pk_bf16_f32 v42, v51, v45
	v_addc_co_u32_e32 v45, vcc, 0, v141, vcc
	v_pk_mul_f32 v[38:39], v[38:39], v[50:51] op_sel_hi:[1,0]
	v_pk_mul_f32 v[36:37], v[36:37], v[50:51] op_sel_hi:[1,0]
	v_max_f32_e32 v32, 0, v32
	v_max_f32_e32 v33, 0, v33
	v_max_f32_e32 v34, 0, v34
	v_cvt_pk_bf16_f32 v43, v46, v43
	global_store_dwordx4 v[44:45], v[40:43], off
	v_max_f32_e32 v35, 0, v35
	v_max_f32_e32 v36, 0, v36
	v_mul_f32_e32 v40, v32, v32
	v_max_f32_e32 v32, 0, v37
	v_mul_f32_e32 v37, v33, v33
	v_max_f32_e32 v33, 0, v38
	v_mul_f32_e32 v38, v34, v34
	v_max_f32_e32 v34, 0, v39
	v_mul_f32_e32 v32, v32, v32
	v_mul_f32_e32 v33, v33, v33
	v_mul_f32_e32 v34, v34, v34
	v_mul_f32_e32 v35, v35, v35
	v_mul_f32_e32 v36, v36, v36
	v_cvt_pk_bf16_f32 v32, v36, v32
	v_cvt_pk_bf16_f32 v33, v33, v34
	v_cvt_pk_bf16_f32 v34, v40, v37
	v_cvt_pk_bf16_f32 v35, v38, v35
	global_store_dwordx4 v[48:49], v[32:35], off offset:256
	s_nop 1
	v_mov_b32_e32 v32, v169
	v_fmamk_f32 v32, v32, 0x3a800000, v235
	s_mov_b64 s[4:5], 0x140000
	v_rsq_f32_e32 v34, v32
	s_nop 0
	v_pk_mul_f32 v[24:25], v[24:25], v[34:35] op_sel_hi:[1,0]
	v_pk_mul_f32 v[28:29], v[28:29], v[34:35] op_sel_hi:[1,0]
	v_pk_mul_f32 v[26:27], v[26:27], v[34:35] op_sel_hi:[1,0]
	v_max_f32_e32 v24, 0, v24
	v_pk_mul_f32 v[30:31], v[30:31], v[34:35] op_sel_hi:[1,0]
	v_max_f32_e32 v28, 0, v28
	v_mul_f32_e32 v35, v24, v24
	v_max_f32_e32 v24, 0, v29
	v_max_f32_e32 v25, 0, v25
	v_max_f32_e32 v26, 0, v26
	v_lshl_add_u64 v[32:33], v[140:141], 0, s[4:5]
	v_mul_f32_e32 v28, v28, v28
	v_mul_f32_e32 v24, v24, v24
	v_mul_f32_e32 v29, v25, v25
	v_max_f32_e32 v25, 0, v30
	v_mul_f32_e32 v30, v26, v26
	v_max_f32_e32 v26, 0, v31
	s_mov_b32 s4, 0x140000
	v_mul_f32_e32 v25, v25, v25
	v_max_f32_e32 v27, 0, v27
	v_mul_f32_e32 v26, v26, v26
	v_cvt_pk_bf16_f32 v24, v28, v24
	v_add_co_u32_e32 v28, vcc, s4, v140
	v_pk_mul_f32 v[18:19], v[18:19], v[34:35] op_sel_hi:[1,0]
	v_pk_mul_f32 v[16:17], v[16:17], v[34:35] op_sel_hi:[1,0]
	v_mul_f32_e32 v27, v27, v27
	v_cvt_pk_bf16_f32 v25, v25, v26
	v_cvt_pk_bf16_f32 v26, v35, v29
	v_addc_co_u32_e32 v29, vcc, 0, v141, vcc
	v_pk_mul_f32 v[22:23], v[22:23], v[34:35] op_sel_hi:[1,0]
	v_pk_mul_f32 v[20:21], v[20:21], v[34:35] op_sel_hi:[1,0]
	v_max_f32_e32 v16, 0, v16
	v_max_f32_e32 v17, 0, v17
	v_max_f32_e32 v18, 0, v18
	v_cvt_pk_bf16_f32 v27, v30, v27
	global_store_dwordx4 v[28:29], v[24:27], off
	v_max_f32_e32 v19, 0, v19
	v_max_f32_e32 v20, 0, v20
	v_mul_f32_e32 v24, v16, v16
	v_max_f32_e32 v16, 0, v21
	v_mul_f32_e32 v21, v17, v17
	v_max_f32_e32 v17, 0, v22
	v_mul_f32_e32 v22, v18, v18
	v_max_f32_e32 v18, 0, v23
	v_mul_f32_e32 v16, v16, v16
	v_mul_f32_e32 v17, v17, v17
	v_mul_f32_e32 v18, v18, v18
	v_mul_f32_e32 v19, v19, v19
	v_mul_f32_e32 v20, v20, v20
	v_cvt_pk_bf16_f32 v16, v20, v16
	v_cvt_pk_bf16_f32 v17, v17, v18
	v_cvt_pk_bf16_f32 v18, v24, v21
	v_cvt_pk_bf16_f32 v19, v22, v19
	global_store_dwordx4 v[32:33], v[16:19], off offset:256
	s_nop 1
	v_mov_b32_e32 v16, v170
	v_fmamk_f32 v16, v16, 0x3a800000, v235
	s_mov_b64 s[4:5], 0x160000
	v_rsq_f32_e32 v16, v16
	s_nop 0
	v_pk_mul_f32 v[8:9], v[8:9], v[16:17] op_sel_hi:[1,0]
	v_pk_mul_f32 v[12:13], v[12:13], v[16:17] op_sel_hi:[1,0]
	v_pk_mul_f32 v[10:11], v[10:11], v[16:17] op_sel_hi:[1,0]
	v_max_f32_e32 v8, 0, v8
	v_pk_mul_f32 v[14:15], v[14:15], v[16:17] op_sel_hi:[1,0]
	v_max_f32_e32 v12, 0, v12
	v_mul_f32_e32 v17, v8, v8
	v_max_f32_e32 v8, 0, v13
	v_max_f32_e32 v9, 0, v9
	v_max_f32_e32 v10, 0, v10
	v_lshl_add_u64 v[18:19], v[140:141], 0, s[4:5]
	v_mul_f32_e32 v12, v12, v12
	v_mul_f32_e32 v8, v8, v8
	v_mul_f32_e32 v13, v9, v9
	v_max_f32_e32 v9, 0, v14
	v_mul_f32_e32 v14, v10, v10
	v_max_f32_e32 v10, 0, v15
	s_mov_b32 s4, 0x160000
	v_mul_f32_e32 v9, v9, v9
	v_max_f32_e32 v11, 0, v11
	v_mul_f32_e32 v10, v10, v10
	v_cvt_pk_bf16_f32 v8, v12, v8
	v_add_co_u32_e32 v12, vcc, s4, v140
	v_pk_mul_f32 v[2:3], v[2:3], v[16:17] op_sel_hi:[1,0]
	v_pk_mul_f32 v[0:1], v[0:1], v[16:17] op_sel_hi:[1,0]
	v_mul_f32_e32 v11, v11, v11
	v_cvt_pk_bf16_f32 v9, v9, v10
	v_cvt_pk_bf16_f32 v10, v17, v13
	v_addc_co_u32_e32 v13, vcc, 0, v141, vcc
	v_pk_mul_f32 v[6:7], v[6:7], v[16:17] op_sel_hi:[1,0]
	v_pk_mul_f32 v[4:5], v[4:5], v[16:17] op_sel_hi:[1,0]
	v_max_f32_e32 v0, 0, v0
	v_max_f32_e32 v1, 0, v1
	v_max_f32_e32 v2, 0, v2
	v_cvt_pk_bf16_f32 v11, v14, v11
	global_store_dwordx4 v[12:13], v[8:11], off
	v_max_f32_e32 v3, 0, v3
	v_max_f32_e32 v4, 0, v4
	v_mul_f32_e32 v8, v0, v0
	v_max_f32_e32 v0, 0, v5
	v_mul_f32_e32 v5, v1, v1
	v_max_f32_e32 v1, 0, v6
	v_mul_f32_e32 v6, v2, v2
	v_max_f32_e32 v2, 0, v7
	v_mul_f32_e32 v0, v0, v0
	v_mul_f32_e32 v1, v1, v1
	v_mul_f32_e32 v2, v2, v2
	v_mul_f32_e32 v3, v3, v3
	s_andn2_b64 vcc, exec, s[38:39]
	v_mul_f32_e32 v4, v4, v4
	v_cvt_pk_bf16_f32 v0, v4, v0
	v_cvt_pk_bf16_f32 v1, v1, v2
	v_cvt_pk_bf16_f32 v2, v8, v5
	v_cvt_pk_bf16_f32 v3, v6, v3
	global_store_dwordx4 v[18:19], v[0:3], off offset:256
	s_cbranch_vccnz .LBB0_1136
	s_andn2_b64 vcc, exec, s[42:43]
	s_cbranch_vccnz .LBB0_1135
	s_barrier
	s_branch .LBB0_1135
